# FoX units: next-unit prefetch (first K/V/cum pair by LDS-DMA + Q/cq into idle VGPRs during the last pair), queue atomic wait deferred
# baseline (speedup 1.0000x reference)
.LBB0_207:
	s_or_b64 exec, exec, s[4:5]
	v_readlane_b32 s4, v253, 19
	s_waitcnt lgkmcnt(0)
	s_barrier
	v_mov_b32_e32 v0, s4
	ds_read_b32 v0, v0
	s_waitcnt lgkmcnt(0)
	v_cmp_lt_i32_e32 vcc, s45, v0
	v_readfirstlane_b32 s38, v0
	s_cbranch_vccnz .LBB0_261
	s_mov_b32 s32, 0
	v_writelane_b32 v255, s42, 61
	s_mov_b32 s21, 0
	s_nop 0
	v_writelane_b32 v255, s43, 62
	s_branch .LBB0_210

.LBB0_210:
	v_mov_b32_e32 v184, 0
	s_and_saveexec_b64 s[4:5], s[42:43]
	s_cbranch_execz .LBB0_214
	s_mov_b64 s[8:9], exec
	v_mbcnt_lo_u32_b32 v0, s8, 0
	v_mbcnt_hi_u32_b32 v0, s9, v0
	v_cmp_eq_u32_e32 vcc, 0, v0
	s_and_saveexec_b64 s[6:7], vcc
	s_cbranch_execz .LBB0_213
	s_bcnt1_i32_b64 s8, s[8:9]
	v_mov_b32_e32 v1, s8
	v_readlane_b32 s8, v255, 59
	v_readlane_b32 s9, v255, 60
	s_nop 4
	global_atomic_add v184, v193, v1, s[8:9] offset:4 sc0
.LBB0_213:
	s_or_b64 exec, exec, s[6:7]
.LBB0_214:
	s_or_b64 exec, exec, s[4:5]
	s_cmpk_gt_i32 s38, 0x3ff
	s_mov_b64 s[4:5], -1
	s_cbranch_scc0 .LBB0_232
	s_add_i32 s4, s38, 0xfffffc00
	v_mov_b32_e32 v2, v216
	s_lshr_b32 s4, s4, 6
	s_sub_i32 s7, 15, s4
	v_readfirstlane_b32 s6, v2
	s_ashr_i32 s9, s6, 6
	s_lshl_b32 s4, s38, 9
	s_and_b32 s28, s38, 7
	s_and_b32 s34, s4, 0x7000
	s_lshl_b32 s4, s7, 8
	s_lshl_b32 s5, s9, 5
	v_and_b32_e32 v3, 31, v2
	s_add_i32 s5, s5, s4
	s_lshl_b32 s8, s28, 7
	v_readlane_b32 s4, v255, 4
	v_or_b32_e32 v0, s5, v3
	s_add_u32 s4, s4, s8
	v_readlane_b32 s5, v255, 5
	s_addc_u32 s5, s5, 0
	v_readlane_b32 s12, v255, 6
	s_add_u32 s12, s12, s8
	v_readlane_b32 s13, v255, 7
	v_and_b32_e32 v1, 63, v2
	s_addc_u32 s13, s13, 0
	v_readlane_b32 s14, v255, 8
	s_add_u32 s18, s14, s8
	v_readlane_b32 s8, v255, 9
	v_or_b32_e32 v1, s34, v1
	s_addc_u32 s19, s8, 0
	v_lshlrev_b32_e32 v192, 10, v1
	s_and_b32 s14, s9, 3
	v_bfe_u32 v1, v2, 2, 4
	v_lshl_add_u64 v[6:7], s[12:13], 0, v[192:193]
	s_lshl_b32 s12, s9, 3
	v_lshl_or_b32 v1, s14, 4, v1
	s_ashr_i32 s13, s12, 31
	v_or_b32_e32 v1, s34, v1
	s_ashr_i32 s15, s6, 8
	v_lshl_add_u64 v[162:163], s[12:13], 1, v[6:7]
	v_lshlrev_b32_e32 v192, 10, v1
	s_lshl_b32 s12, s15, 5
	v_lshl_add_u64 v[6:7], s[18:19], 0, v[192:193]
	s_ashr_i32 s13, s12, 31
	v_lshl_add_u64 v[8:9], s[12:13], 1, v[6:7]
	v_lshlrev_b32_e32 v6, 3, v2
	s_lshl_b32 s7, s7, 2
	v_and_b32_e32 v5, 24, v6
	v_sub_u32_e64 v10, s7, 8 clamp
	v_lshlrev_b32_e32 v192, 1, v5
	v_lshl_add_u64 v[166:167], v[8:9], 0, v[192:193]
	v_lshlrev_b32_e32 v192, 16, v10
	s_lshl_b32 s29, s9, 10
	v_lshl_add_u64 v[8:9], v[162:163], 0, v[192:193]
	s_add_i32 s29, s29, 0
	s_mov_b32 s9, m0
	s_mov_b32 m0, s29
	s_nop 0
	global_load_lds_dwordx4 v[8:9], off
	s_mov_b32 m0, s9
	s_lshl_b32 s9, s15, 12
	s_lshl_b32 s12, s14, 10
	s_or_b32 s9, s12, s9
	s_add_i32 s9, s9, 0
	s_max_u32 s8, s7, 8
	v_lshl_add_u64 v[8:9], v[166:167], 0, v[192:193]
	s_add_i32 s36, s9, 0xc000
	s_mov_b32 s12, m0
	s_mov_b32 m0, s36
	s_nop 0
	global_load_lds_dwordx4 v[8:9], off
	s_mov_b32 m0, s12
	s_add_i32 s12, s8, -7
	s_mov_b32 s13, s35
	s_lshl_b64 s[12:13], s[12:13], 16
	v_lshl_add_u64 v[8:9], v[162:163], 0, s[12:13]
	v_ashrrev_i32_e32 v1, 31, v0
	s_add_i32 s14, s29, 0x3000
	s_mov_b32 s15, m0
	s_mov_b32 m0, s14
	s_nop 0
	global_load_lds_dwordx4 v[8:9], off
	s_mov_b32 m0, s15
	v_lshl_add_u64 v[8:9], v[166:167], 0, s[12:13]
	v_lshl_add_u64 v[164:165], v[0:1], 0, s[34:35]
	v_bfe_u32 v4, v2, 5, 1
	s_add_i32 s9, s9, 0xe000
	s_mov_b32 s12, m0
	s_mov_b32 m0, s9
	s_nop 0
	global_load_lds_dwordx4 v[8:9], off
	s_mov_b32 m0, s12
	v_lshlrev_b64 v[8:9], 10, v[164:165]
	v_lshl_add_u64 v[8:9], s[4:5], 0, v[8:9]
	v_lshlrev_b32_e32 v192, 4, v4
	v_lshl_add_u64 v[8:9], v[8:9], 0, v[192:193]
	global_load_dwordx4 v[112:115], v[8:9], off
	global_load_dwordx4 v[116:119], v[8:9], off offset:32
	global_load_dwordx4 v[120:123], v[8:9], off offset:64
	global_load_dwordx4 v[124:127], v[8:9], off offset:96
	s_movk_i32 s4, 0x140
	s_mov_b32 s20, s90
	v_readfirstlane_b32 s34, v10
	v_cmp_gt_i32_e32 vcc, s4, v2
	s_and_b32 s4, s38, 63
	s_lshl_b32 s4, s4, 2
	s_or_b32 s4, s4, 0x27e0
	v_mov_b32_e32 v11, s4
	v_readlane_b32 s12, v253, 26
	v_readlane_b32 s13, v253, 27
	s_nop 4
	global_load_dword v11, v11, s[12:13]
	s_and_saveexec_b64 s[4:5], vcc
	s_cbranch_execz .Lt3_skiprel
	v_or_b32_e32 v6, s28, v6
	v_ashrrev_i32_e32 v7, 31, v6
	v_lshl_add_u64 v[6:7], v[6:7], 2, s[12:13]
	global_load_dword v1, v[6:7], off

.LBB0_235:
	s_lshl_b32 s5, s38, 9
	v_mov_b32_e32 v3, v216
	s_and_b32 s34, s5, 0x7000
	s_lshl_b32 s5, s38, 6
	s_and_b32 s5, s5, 0x1c0
	v_readfirstlane_b32 s18, v3
	s_and_b32 s4, s38, 63
	s_ashr_i32 s19, s18, 6
	s_lshl_b32 s40, s5, 1
	v_readlane_b32 s5, v255, 10
	s_add_u32 s6, s5, s40
	v_readlane_b32 s5, v255, 11
	s_addc_u32 s7, s5, 0
	v_readlane_b32 s5, v255, 12
	v_and_b32_e32 v4, 63, v3
	s_add_u32 s8, s5, s40
	v_readlane_b32 s5, v255, 13
	s_addc_u32 s9, s5, 0
	s_lshl_b32 s4, s4, 14
	v_readlane_b32 s12, v255, 0
	v_or_b32_e32 v0, s34, v4
	v_readlane_b32 s13, v255, 1
	s_add_u32 s4, s12, s4
	v_lshlrev_b32_e32 v192, 10, v0
	s_addc_u32 s5, s13, 0
	v_lshl_add_u64 v[0:1], s[6:7], 0, v[192:193]
	s_lshl_b32 s6, s19, 3
	s_ashr_i32 s7, s6, 31
	v_lshl_add_u64 v[128:129], s[6:7], 1, v[0:1]
	s_and_b32 s12, s19, 3
	v_bfe_u32 v0, v3, 2, 4
	v_lshl_or_b32 v0, s12, 4, v0
	v_or_b32_e32 v0, s34, v0
	v_lshlrev_b32_e32 v192, 10, v0
	v_lshl_add_u64 v[0:1], s[8:9], 0, v[192:193]
	s_ashr_i32 s8, s18, 8
	s_lshl_b32 s6, s8, 5
	s_ashr_i32 s7, s6, 31
	s_lshl_b32 s41, s19, 10
	v_lshl_add_u64 v[0:1], s[6:7], 1, v[0:1]
	s_add_i32 s41, s41, 0
	s_cmp_lg_u32 s32, 0
	s_cbranch_scc1 .Lpf2_s0
	s_mov_b32 s6, m0
	s_mov_b32 m0, s41
	s_nop 0
	global_load_lds_dwordx4 v[128:129], off
	s_mov_b32 m0, s6
.Lpf2_s0:
	s_lshl_b32 s6, s8, 12
	s_lshl_b32 s7, s12, 10
	s_or_b32 s6, s7, s6
	v_lshlrev_b32_e32 v2, 3, v3
	s_add_i32 s8, s6, 0
	v_and_b32_e32 v2, 24, v2
	s_add_i32 s36, s8, 0xc000
	v_lshlrev_b32_e32 v192, 1, v2
	v_lshl_add_u64 v[130:131], v[0:1], 0, v[192:193]
	s_cmp_lg_u32 s32, 0
	s_cbranch_scc1 .Lpf2_s1
	s_mov_b32 s6, m0
	s_mov_b32 m0, s36
	s_nop 0
	global_load_lds_dwordx4 v[130:131], off
	s_mov_b32 m0, s6
.Lpf2_s1:
	s_cmp_eq_u32 s19, 7
	s_cselect_b64 s[28:29], -1, 0
	s_cmp_lg_u32 s19, 7
	s_cselect_b64 s[6:7], -1, 0
	s_and_b64 vcc, exec, s[6:7]
	v_lshlrev_b32_e32 v192, 4, v4
	s_cbranch_vccnz .LBB0_237
	v_lshl_add_u64 v[0:1], s[4:5], 0, v[192:193]
	v_readlane_b32 s12, v253, 20
	s_cmp_lg_u32 s32, 0
	s_cbranch_scc1 .Lpf2_s2
	s_mov_b32 s9, m0
	s_mov_b32 m0, s12
	s_nop 0
	global_load_lds_dwordx4 v[0:1], off
	s_mov_b32 m0, s9
.Lpf2_s2:
.LBB0_237:
	s_mov_b64 s[14:15], 0x10000
	v_lshl_add_u64 v[0:1], v[128:129], 0, s[14:15]
	s_add_i32 s9, s41, 0x3000
	s_cmp_lg_u32 s32, 0
	s_cbranch_scc1 .Lpf2_s3
	s_mov_b32 s12, m0
	s_mov_b32 m0, s9
	s_nop 0
	global_load_lds_dwordx4 v[0:1], off
	s_mov_b32 m0, s12
.Lpf2_s3:
	v_lshl_add_u64 v[0:1], v[130:131], 0, s[14:15]
	s_add_i32 s8, s8, 0xe000
	s_cmp_lg_u32 s32, 0
	s_cbranch_scc1 .Lpf2_s4
	s_mov_b32 s9, m0
	s_mov_b32 m0, s8
	s_nop 0
	global_load_lds_dwordx4 v[0:1], off
	s_mov_b32 m0, s9
.Lpf2_s4:
	s_mov_b64 s[8:9], -1
	s_andn2_b64 vcc, exec, s[6:7]
	v_lshlrev_b32_e32 v0, 2, v4
	s_cbranch_vccnz .LBB0_239
	v_mov_b32_e32 v1, v193
	s_mov_b64 s[8:9], 0
.LBB0_239:
	v_writelane_b32 v255, s21, 63
	s_mov_b32 s15, s93
	s_andn2_b64 vcc, exec, s[8:9]
	s_cbranch_vccnz .LBB0_241
	v_lshl_add_u64 v[6:7], s[4:5], 0, v[192:193]
	s_mov_b64 s[6:7], 0x100
	v_lshl_add_u64 v[6:7], v[6:7], 0, s[6:7]
	v_readlane_b32 s7, v253, 21
	s_cmp_lg_u32 s32, 0
	s_cbranch_scc1 .Lpf2_s5
	s_mov_b32 s6, m0
	s_mov_b32 m0, s7
	s_nop 0
	global_load_lds_dwordx4 v[6:7], off
	s_mov_b32 m0, s6
.Lpf2_s5:
	v_mov_b32_e32 v1, v193
.LBB0_241:
	s_ashr_i32 s6, s38, 6
	s_sub_i32 s8, 15, s6
	s_lshl_b32 s6, s8, 8
	s_lshl_b32 s7, s19, 5
	v_and_b32_e32 v8, 31, v3
	s_add_i32 s7, s7, s6
	v_lshrrev_b32_e32 v9, 5, v4
	v_or_b32_e32 v4, s7, v8
	v_readlane_b32 s6, v254, 19
	v_ashrrev_i32_e32 v5, 31, v4
	v_readlane_b32 s7, v254, 20
	s_add_u32 s6, s6, s40
	v_lshl_add_u64 v[132:133], v[4:5], 0, s[34:35]
	s_addc_u32 s7, s7, 0
	v_lshlrev_b64 v[6:7], 10, v[132:133]
	v_lshl_add_u64 v[6:7], s[6:7], 0, v[6:7]
	v_lshlrev_b32_e32 v192, 4, v9
	v_lshl_add_u64 v[6:7], v[6:7], 0, v[192:193]
	s_cmp_lg_u32 s32, 0
	s_cbranch_scc1 .Lpf2_q1
	global_load_dwordx4 v[80:83], v[6:7], off
	global_load_dwordx4 v[84:87], v[6:7], off offset:32
	global_load_dwordx4 v[88:91], v[6:7], off offset:64
	global_load_dwordx4 v[92:95], v[6:7], off offset:96
	s_branch .Lpf2_q2
.Lpf2_q1:
	v_mov_b32_e32 v80, v242
	v_mov_b32_e32 v81, v243
	v_mov_b32_e32 v82, v244
	v_mov_b32_e32 v83, v245
	v_mov_b32_e32 v84, v246
	v_mov_b32_e32 v85, v247
	v_mov_b32_e32 v86, v248
	v_mov_b32_e32 v87, v249
	v_mov_b32_e32 v88, v212
	v_mov_b32_e32 v89, v213
	v_mov_b32_e32 v90, v214
	v_mov_b32_e32 v91, v215
	v_mov_b32_e32 v92, v250
	v_mov_b32_e32 v93, v251
	v_mov_b32_e32 v94, v208
	v_mov_b32_e32 v95, v209
.Lpf2_q2:
	v_lshrrev_b32_e32 v7, 2, v3
	v_lshl_add_u64 v[134:135], v[0:1], 2, s[4:5]
	v_lshl_add_u64 v[0:1], v[4:5], 2, s[4:5]
	s_cmp_lg_u32 s32, 0
	s_cbranch_scc1 .Lpf2_c1
	global_load_dword v32, v[0:1], off
	s_branch .Lpf2_c2
.Lpf2_c1:
	v_mov_b32_e32 v32, v211
.Lpf2_c2:
	s_mov_b32 s32, 0
	v_lshlrev_b32_e32 v160, 2, v9
	v_readlane_b32 s4, v253, 20
	v_lshlrev_b32_e32 v3, 1, v3
	v_and_or_b32 v5, v7, 3, v160
	v_add_u32_e32 v141, s4, v192
	s_lshl_b32 s4, s8, 2
	s_ashr_i32 s18, s18, 7
	v_and_b32_e32 v3, 32, v3
	s_add_i32 s18, s18, s4
	v_mov_b32_e32 v6, v193
	s_add_i32 s4, s4, 4
	v_mov_b32_e32 v192, v193
	v_mov_b32_e32 v194, v193
	v_mov_b32_e32 v195, v193
	v_mov_b32_e32 v196, v193
	v_mov_b32_e32 v197, v193
	v_mov_b32_e32 v198, v193
	v_mov_b32_e32 v199, v193
	v_mov_b32_e32 v200, v193
	v_mov_b32_e32 v201, v193
	v_mov_b32_e32 v202, v193
	v_mov_b32_e32 v203, v193
	v_mov_b32_e32 v204, v193
	v_mov_b32_e32 v205, v193
	v_mov_b32_e32 v206, v193
	v_mov_b32_e32 v207, v193
	s_lshr_b32 s19, s4, 1
	s_mov_b32 s37, 0
	v_mov_b32_e32 v143, 0
	s_waitcnt vmcnt(3)
	s_waitcnt vmcnt(2)
	s_waitcnt vmcnt(1)
	s_waitcnt vmcnt(0)
	v_lshlrev_b32_e32 v0, 10, v9
	v_lshlrev_b32_e32 v1, 4, v8
	v_add3_u32 v140, 0, v0, v1
	v_lshl_add_u32 v0, v5, 6, 0
	v_add3_u32 v142, v0, v3, v2
	v_lshl_or_b32 v0, s18, 6, v160
	v_cmp_gt_i32_e64 s[42:43], v0, v4
	v_cmp_lt_i32_e64 s[44:45], v0, v4
	v_or_b32_e32 v1, 3, v0
	v_or_b32_e32 v2, 2, v0
	v_or_b32_e32 v3, 9, v0
	v_or_b32_e32 v5, 8, v0
	v_or_b32_e32 v7, 11, v0
	v_or_b32_e32 v8, 10, v0
	v_or_b32_e32 v9, 17, v0
	v_or_b32_e32 v10, 16, v0
	v_or_b32_e32 v11, 19, v0
	v_or_b32_e32 v12, 18, v0
	v_or_b32_e32 v13, 25, v0
	v_or_b32_e32 v14, 24, v0
	v_or_b32_e32 v15, 27, v0
	v_or_b32_e32 v16, 26, v0
	v_or_b32_e32 v17, 32, v0
	v_or_b32_e32 v18, 33, v0
	v_or_b32_e32 v19, 34, v0
	v_or_b32_e32 v20, 35, v0
	v_or_b32_e32 v21, 40, v0
	v_or_b32_e32 v22, 41, v0
	v_or_b32_e32 v23, 42, v0
	v_or_b32_e32 v24, 43, v0
	v_or_b32_e32 v25, 48, v0
	v_or_b32_e32 v26, 49, v0
	v_or_b32_e32 v27, 50, v0
	v_or_b32_e32 v28, 51, v0
	v_or_b32_e32 v29, 56, v0
	v_or_b32_e32 v30, 57, v0
	v_or_b32_e32 v31, 58, v0
	v_or_b32_e32 v0, 59, v0
	s_waitcnt vmcnt(0)
	s_waitcnt vmcnt(0)
	v_readfirstlane_b32 vcc_lo, v216
	s_cmp_lt_u32 vcc_lo, 64
	s_cbranch_scc0 .Lpf2_nosu
	v_readfirstlane_b32 vcc_lo, v184
	v_readlane_b32 vcc_hi, v255, 63
	s_xor_b32 vcc_hi, vcc_hi, 1
	s_lshl_b32 vcc_hi, vcc_hi, 2
	s_add_i32 vcc_hi, vcc_hi, 0x15500
	v_mov_b32_e32 v48, vcc_hi
	v_mov_b32_e32 v49, vcc_lo
	ds_write_b32 v48, v49
.Lpf2_nosu:
	s_waitcnt vmcnt(0) lgkmcnt(0)
	s_barrier
	v_cmp_gt_i32_e64 s[46:47], v1, v4
	v_cmp_gt_i32_e64 s[48:49], v2, v4
	v_cmp_gt_i32_e64 s[50:51], v3, v4
	v_cmp_gt_i32_e64 s[52:53], v5, v4
	v_cmp_gt_i32_e64 s[54:55], v7, v4
	v_cmp_gt_i32_e64 s[56:57], v8, v4
	v_cmp_gt_i32_e64 s[58:59], v9, v4
	v_cmp_gt_i32_e64 s[60:61], v10, v4
	v_cmp_gt_i32_e64 s[62:63], v11, v4
	v_cmp_gt_i32_e64 s[64:65], v12, v4
	v_cmp_gt_i32_e64 s[66:67], v13, v4
	v_cmp_gt_i32_e64 s[68:69], v14, v4
	v_cmp_gt_i32_e64 s[70:71], v15, v4
	v_cmp_gt_i32_e64 s[72:73], v16, v4
	v_cmp_gt_i32_e64 s[74:75], v0, v4
	v_cmp_gt_i32_e64 s[76:77], v31, v4
	v_cmp_gt_i32_e64 s[78:79], v30, v4
	v_cmp_gt_i32_e64 s[80:81], v29, v4
	v_cmp_gt_i32_e64 s[82:83], v28, v4
	v_cmp_gt_i32_e64 s[84:85], v27, v4
	v_cmp_gt_i32_e64 s[86:87], v26, v4
	v_cmp_gt_i32_e64 s[88:89], v25, v4
	v_cmp_gt_i32_e64 s[90:91], v24, v4
	v_cmp_gt_i32_e64 s[92:93], v23, v4
	v_cmp_gt_i32_e64 s[94:95], v22, v4
	v_cmp_gt_i32_e64 s[96:97], v21, v4
	v_cmp_gt_i32_e64 s[98:99], v20, v4
	v_cmp_gt_i32_e64 s[38:39], v19, v4
	v_cmp_gt_i32_e64 s[4:5], v18, v4
	v_cmp_gt_i32_e64 s[6:7], v17, v4
	v_mov_b64_e32 v[16:17], v[192:193]
	v_mov_b64_e32 v[0:1], v[192:193]
	v_mov_b32_e32 v33, v32
	v_mov_b32_e32 v34, v32
	v_mov_b32_e32 v35, v32
	v_mov_b32_e32 v36, v32
	v_mov_b32_e32 v37, v32
	v_mov_b32_e32 v38, v32
	v_mov_b32_e32 v39, v32
	v_mov_b32_e32 v40, v32
	v_mov_b32_e32 v41, v32
	v_mov_b32_e32 v42, v32
	v_mov_b32_e32 v43, v32
	v_mov_b32_e32 v44, v32
	v_mov_b32_e32 v45, v32
	v_mov_b32_e32 v46, v32
	v_mov_b32_e32 v47, v32
	v_mov_b64_e32 v[18:19], v[194:195]
	v_mov_b64_e32 v[20:21], v[196:197]
	v_mov_b64_e32 v[22:23], v[198:199]
	v_mov_b64_e32 v[24:25], v[200:201]
	v_mov_b64_e32 v[26:27], v[202:203]
	v_mov_b64_e32 v[28:29], v[204:205]
	v_mov_b64_e32 v[30:31], v[206:207]
	v_mov_b64_e32 v[2:3], v[194:195]
	v_mov_b64_e32 v[4:5], v[196:197]
	v_mov_b64_e32 v[6:7], v[198:199]
	v_mov_b64_e32 v[8:9], v[200:201]
	v_mov_b64_e32 v[10:11], v[202:203]
	v_mov_b64_e32 v[12:13], v[204:205]
	v_mov_b64_e32 v[14:15], v[206:207]
	s_branch .LBB0_243
.Lpf2_block:
	v_readlane_b32 s8, v255, 63
	s_xor_b32 s8, s8, 1
	s_lshl_b32 s8, s8, 2
	s_add_i32 s8, s8, 0x15500
	v_mov_b32_e32 v48, s8
	ds_read_b32 v48, v48
	s_waitcnt lgkmcnt(0)
	v_readfirstlane_b32 s8, v48
	s_cmp_lt_u32 s8, 0x400
	s_cbranch_scc0 .LBB0_248
	s_mov_b32 s32, 1
	s_and_b32 s9, s8, 63
	s_lshr_b32 s8, s8, 6
	s_sub_i32 s8, 15, s8
	s_lshr_b32 s12, s9, 3
	s_lshl_b32 s12, s12, 22
	s_and_b32 s13, s9, 7
	s_lshl_b32 s13, s13, 7
	s_add_u32 s12, s12, s13
	v_readlane_b32 vcc_lo, v255, 10
	v_readlane_b32 vcc_hi, v255, 11
	s_add_u32 vcc_lo, vcc_lo, s12
	s_addc_u32 vcc_hi, vcc_hi, 0
	v_and_b32_e32 v48, 63, v216
	v_lshrrev_b32_e32 v49, 6, v216
	v_lshlrev_b32_e32 v48, 10, v48
	v_lshl_or_b32 v48, v49, 4, v48
	s_mov_b32 m0, s41
	s_nop 0
	global_load_lds_dwordx4 v48, vcc
	s_add_u32 vcc_lo, vcc_lo, 0x10000
	s_addc_u32 vcc_hi, vcc_hi, 0
	s_add_i32 m0, s41, 0x3000
	s_nop 0
	global_load_lds_dwordx4 v48, vcc
	v_readlane_b32 vcc_lo, v255, 12
	v_readlane_b32 vcc_hi, v255, 13
	s_add_u32 vcc_lo, vcc_lo, s12
	s_addc_u32 vcc_hi, vcc_hi, 0
	v_and_b32_e32 v50, 63, v216
	v_lshrrev_b32_e32 v51, 2, v50
	v_and_b32_e32 v52, 3, v49
	v_lshl_or_b32 v51, v52, 4, v51
	v_lshlrev_b32_e32 v51, 10, v51
	v_lshrrev_b32_e32 v52, 2, v49
	v_lshl_or_b32 v51, v52, 6, v51
	v_and_b32_e32 v50, 3, v50
	v_lshl_or_b32 v50, v50, 4, v51
	s_mov_b32 m0, s36
	s_nop 0
	global_load_lds_dwordx4 v50, vcc
	s_add_u32 vcc_lo, vcc_lo, 0x10000
	s_addc_u32 vcc_hi, vcc_hi, 0
	s_add_i32 m0, s36, 0x2000
	s_nop 0
	global_load_lds_dwordx4 v50, vcc
	s_cmp_eq_u64 s[28:29], 0
	s_cbranch_scc1 .Lpf2_nocum
	v_readlane_b32 vcc_lo, v255, 0
	v_readlane_b32 vcc_hi, v255, 1
	s_lshl_b32 s12, s9, 14
	s_add_u32 vcc_lo, vcc_lo, s12
	s_addc_u32 vcc_hi, vcc_hi, 0
	v_and_b32_e32 v50, 63, v216
	v_lshlrev_b32_e32 v50, 4, v50
	s_mov_b32 m0, 0x14500
	s_nop 0
	global_load_lds_dwordx4 v50, vcc
	s_mov_b32 m0, 0x14900
	v_add_u32_e32 v50, 0x100, v50
	global_load_lds_dwordx4 v50, vcc
.Lpf2_nocum:
	v_readlane_b32 vcc_lo, v254, 19
	v_readlane_b32 vcc_hi, v254, 20
	s_lshr_b32 s12, s9, 3
	s_lshl_b32 s12, s12, 12
	s_lshl_b32 s14, s8, 8
	s_add_i32 s12, s12, s14
	s_lshl_b32 s12, s12, 10
	s_add_u32 s12, s12, s13
	s_add_u32 vcc_lo, vcc_lo, s12
	s_addc_u32 vcc_hi, vcc_hi, 0
	v_and_b32_e32 v50, 31, v216
	v_lshl_or_b32 v50, v49, 5, v50
	v_lshlrev_b32_e32 v51, 10, v50
	v_bfe_u32 v52, v216, 5, 1
	v_lshl_or_b32 v51, v52, 4, v51
	global_load_dwordx4 v[242:245], v51, vcc
	global_load_dwordx4 v[246:249], v51, vcc offset:32
	global_load_dwordx4 v[212:215], v51, vcc offset:64
	global_load_dwordx2 v[250:251], v51, vcc offset:96
	global_load_dwordx2 v[208:209], v51, vcc offset:104
	v_readlane_b32 vcc_lo, v255, 0
	v_readlane_b32 vcc_hi, v255, 1
	s_lshl_b32 s12, s9, 14
	s_lshl_b32 s14, s8, 10
	s_add_i32 s12, s12, s14
	s_add_u32 vcc_lo, vcc_lo, s12
	s_addc_u32 vcc_hi, vcc_hi, 0
	v_lshlrev_b32_e32 v50, 2, v50
	global_load_dword v211, v50, vcc
	s_branch .LBB0_248

.LBB0_259:
	v_div_scale_f32 v35, s[4:5], v34, v34, 1.0
	v_rcp_f32_e32 v36, v35
	v_div_scale_f32 v37, vcc, 1.0, v34, 1.0
	v_mov_b32_e32 v161, v193
	v_fma_f32 v38, -v35, v36, 1.0
	v_fmac_f32_e32 v36, v38, v36
	v_mul_f32_e32 v38, v37, v36
	v_fma_f32 v39, -v35, v38, v37
	v_fmac_f32_e32 v38, v39, v36
	v_fma_f32 v35, -v35, v38, v37
	v_div_fmas_f32 v35, v35, v36, v38
	v_div_fixup_f32 v34, v35, v34, 1.0
	v_pk_mul_f32 v[16:17], v[16:17], v[34:35] op_sel_hi:[1,0]
	v_pk_mul_f32 v[18:19], v[18:19], v[34:35] op_sel_hi:[1,0]
	v_pk_mul_f32 v[0:1], v[34:35], v[0:1] op_sel_hi:[0,1]
	v_pk_mul_f32 v[2:3], v[34:35], v[2:3] op_sel_hi:[0,1]
	v_lshl_add_u64 v[32:33], v[160:161], 1, v[32:33]
	v_cvt_pk_bf16_f32 v16, v16, v17
	v_cvt_pk_bf16_f32 v17, v18, v19
	v_cvt_pk_bf16_f32 v0, v0, v1
	v_cvt_pk_bf16_f32 v1, v2, v3
	global_store_dwordx2 v[32:33], v[16:17], off
	global_store_dwordx2 v[32:33], v[0:1], off offset:64
	v_pk_mul_f32 v[0:1], v[20:21], v[34:35] op_sel_hi:[1,0]
	v_pk_mul_f32 v[2:3], v[22:23], v[34:35] op_sel_hi:[1,0]
	v_cvt_pk_bf16_f32 v0, v0, v1
	v_cvt_pk_bf16_f32 v1, v2, v3
	v_pk_mul_f32 v[2:3], v[34:35], v[4:5] op_sel_hi:[0,1]
	v_pk_mul_f32 v[4:5], v[34:35], v[6:7] op_sel_hi:[0,1]
	v_cvt_pk_bf16_f32 v2, v2, v3
	v_cvt_pk_bf16_f32 v3, v4, v5
	global_store_dwordx2 v[32:33], v[0:1], off offset:16
	global_store_dwordx2 v[32:33], v[2:3], off offset:80
	v_pk_mul_f32 v[0:1], v[24:25], v[34:35] op_sel_hi:[1,0]
	v_pk_mul_f32 v[2:3], v[26:27], v[34:35] op_sel_hi:[1,0]
	v_cvt_pk_bf16_f32 v0, v0, v1
	v_cvt_pk_bf16_f32 v1, v2, v3
	v_pk_mul_f32 v[2:3], v[34:35], v[8:9] op_sel_hi:[0,1]
	v_pk_mul_f32 v[4:5], v[34:35], v[10:11] op_sel_hi:[0,1]
	v_cvt_pk_bf16_f32 v2, v2, v3
	v_cvt_pk_bf16_f32 v3, v4, v5
	global_store_dwordx2 v[32:33], v[0:1], off offset:32
	global_store_dwordx2 v[32:33], v[2:3], off offset:96
	v_pk_mul_f32 v[0:1], v[28:29], v[34:35] op_sel_hi:[1,0]
	v_pk_mul_f32 v[2:3], v[30:31], v[34:35] op_sel_hi:[1,0]
	v_cvt_pk_bf16_f32 v0, v0, v1
	v_cvt_pk_bf16_f32 v1, v2, v3
	v_pk_mul_f32 v[2:3], v[34:35], v[12:13] op_sel_hi:[0,1]
	v_pk_mul_f32 v[4:5], v[34:35], v[14:15] op_sel_hi:[0,1]
	s_xor_b32 s21, s21, 1
	v_cvt_pk_bf16_f32 v2, v2, v3
	v_cvt_pk_bf16_f32 v3, v4, v5
	global_store_dwordx2 v[32:33], v[0:1], off offset:48
	global_store_dwordx2 v[32:33], v[2:3], off offset:112
	s_and_saveexec_b64 s[4:5], s[42:43]
	s_cbranch_execz .LBB0_209
	s_lshl_b32 s6, s21, 2
	s_add_i32 s6, s6, 0
	s_add_i32 s6, s6, 0x15500
	v_mov_b32_e32 v0, s6
	s_waitcnt vmcnt(0)
	ds_write_b32 v0, v184
	s_branch .LBB0_209

.LBB0_272:
	v_mov_b32_e32 v146, 0
	s_and_saveexec_b64 s[4:5], s[40:41]
	s_cbranch_execz .LBB0_276
	s_mov_b64 s[28:29], exec
	v_mbcnt_lo_u32_b32 v0, s28, 0
	v_mbcnt_hi_u32_b32 v0, s29, v0
	v_cmp_eq_u32_e32 vcc, 0, v0
	s_and_saveexec_b64 s[8:9], vcc
	s_cbranch_execz .LBB0_275
	s_bcnt1_i32_b64 s12, s[28:29]
	v_mov_b32_e32 v1, s12
	global_atomic_add v146, v193, v1, s[6:7] sc0
.LBB0_275:
	s_or_b64 exec, exec, s[8:9]
.LBB0_276:
	s_or_b64 exec, exec, s[4:5]
	s_cmpk_gt_i32 s37, 0x3ff
	s_mov_b64 s[4:5], -1
	s_cbranch_scc0 .LBB0_288
	s_add_i32 s4, s37, 0xfffffc00
	s_lshr_b32 s4, s4, 5
	v_mov_b32_e32 v0, v216
	s_sub_i32 s29, 31, s4
	s_lshl_b32 s5, s37, 1
	v_readfirstlane_b32 s4, v0
	s_ashr_i32 s34, s4, 6
	s_ashr_i32 s36, s4, 8
	s_lshl_b32 s4, s37, 10
	s_and_b32 s5, s5, 6
	s_and_b32 s42, s4, 0x7000
	s_and_b32 s4, s34, 3
	s_add_i32 s28, s36, s5
	s_lshl_b32 s5, s29, 7
	s_lshl_b32 s8, s4, 5
	s_or_b32 s5, s8, s5
	s_lshl_b32 s8, s28, 6
	v_and_b32_e32 v1, 31, v0
	s_ashr_i32 s9, s8, 31
	v_or_b32_e32 v3, s5, v1
	s_lshl_b64 s[12:13], s[8:9], 1
	v_readlane_b32 s5, v255, 14
	s_add_u32 s12, s5, s12
	v_readlane_b32 s5, v255, 15
	s_addc_u32 s13, s5, s13
	s_lshl_b32 s5, s28, 4
	s_and_b32 s18, s5, 0xffffffc0
	s_ashr_i32 s19, s18, 31
	v_and_b32_e32 v4, 63, v0
	s_lshl_b64 s[18:19], s[18:19], 1
	v_readlane_b32 s5, v255, 16
	s_add_u32 s20, s5, s18
	v_readlane_b32 s5, v255, 17
	v_or_b32_e32 v4, s42, v4
	s_addc_u32 s21, s5, s19
	v_readlane_b32 s5, v255, 18
	v_mul_u32_u24_e32 v4, 0x600, v4
	s_add_u32 s38, s5, s18
	v_readlane_b32 s5, v255, 19
	v_lshlrev_b32_e32 v192, 1, v4
	s_addc_u32 s39, s5, s19
	v_lshl_add_u64 v[4:5], s[20:21], 0, v[192:193]
	s_lshl_b32 s20, s34, 3
	s_ashr_i32 s21, s20, 31
	v_lshl_add_u64 v[128:129], s[20:21], 1, v[4:5]
	v_bfe_u32 v4, v0, 2, 4
	v_lshl_or_b32 v4, s4, 4, v4
	v_or_b32_e32 v4, s42, v4
	v_mul_u32_u24_e32 v4, 0x600, v4
	v_lshlrev_b32_e32 v192, 1, v4
	s_lshl_b32 s20, s36, 5
	v_lshl_add_u64 v[4:5], s[38:39], 0, v[192:193]
	s_ashr_i32 s21, s20, 31
	v_lshl_add_u64 v[6:7], s[20:21], 1, v[4:5]
	v_lshlrev_b32_e32 v4, 3, v0
	s_lshl_b32 s5, s29, 1
	v_and_b32_e32 v4, 24, v4
	v_sub_u32_e64 v140, s5, 2 clamp
	v_lshlrev_b32_e32 v192, 1, v4
	s_mov_b32 s14, 0x30000
	v_lshl_add_u64 v[130:131], v[6:7], 0, v[192:193]
	v_mad_u64_u32 v[6:7], s[20:21], v140, s14, v[128:129]
	s_lshl_b32 s19, s34, 10
	s_add_i32 s19, s19, 0
	s_mov_b32 s20, m0
	s_mov_b32 m0, s19
	s_nop 0
	global_load_lds_dwordx4 v[6:7], off
	s_mov_b32 m0, s20
	s_max_u32 s18, s5, 2
	v_mad_u64_u32 v[6:7], s[20:21], v140, s14, v[130:131]
	s_lshl_b32 s20, s36, 12
	s_lshl_b32 s21, s4, 10
	s_or_b32 s20, s21, s20
	s_add_i32 s21, s20, 0
	s_add_i32 s20, s21, 0xc000
	s_mov_b32 s29, m0
	s_mov_b32 m0, s20
	s_nop 0
	global_load_lds_dwordx4 v[6:7], off
	s_mov_b32 m0, s29
	s_add_i32 s29, s18, -1
	v_mad_u64_u32 v[6:7], s[38:39], s29, v230, v[128:129]
	s_add_i32 s34, s19, 0x3000
	s_mov_b32 s36, m0
	s_mov_b32 m0, s34
	s_nop 0
	global_load_lds_dwordx4 v[6:7], off
	s_mov_b32 m0, s36
	v_mad_u64_u32 v[6:7], s[38:39], s29, v230, v[130:131]
	v_bfe_u32 v2, v0, 5, 1
	s_add_i32 s21, s21, 0xe000
	s_mov_b32 s29, m0
	s_mov_b32 m0, s21
	s_nop 0
	global_load_lds_dwordx4 v[6:7], off
	s_mov_b32 m0, s29
	v_or_b32_e32 v137, s42, v3
	v_mov_b64_e32 v[6:7], s[12:13]
	s_movk_i32 s12, 0xc00
	v_mad_u64_u32 v[6:7], s[12:13], v137, s12, v[6:7]
	v_lshlrev_b32_e32 v192, 4, v2
	v_lshl_add_u64 v[6:7], v[6:7], 0, v[192:193]
	global_load_dwordx4 v[80:83], v[6:7], off
	global_load_dwordx4 v[84:87], v[6:7], off offset:32
	global_load_dwordx4 v[88:91], v[6:7], off offset:64
	global_load_dwordx4 v[92:95], v[6:7], off offset:96
	v_mov_b32_e32 v32, 0
	v_mov_b32_e32 v5, 0
	s_sub_i32 s12, s5, s18
	s_add_i32 s12, s12, 4
	s_ashr_i32 s21, s12, 1
	v_mov_b32_e32 v141, 0
	v_lshlrev_b32_e32 v136, 2, v2
	s_cmp_lt_i32 s21, 1
	s_waitcnt vmcnt(3)
	s_waitcnt vmcnt(2)
	s_waitcnt vmcnt(1)
	s_waitcnt vmcnt(0)
	s_waitcnt vmcnt(0) lgkmcnt(0)
	s_barrier
	s_cbranch_scc1 .LBB0_289
	s_add_i32 s12, s28, 1
	v_cvt_f32_i32_e32 v5, s12
	v_cvt_f32_u32_e32 v142, v3
	s_lshr_b32 s4, s4, 1
	v_lshlrev_b32_e32 v1, 4, v1
	v_exp_f32_e64 v3, -v5
	v_lshlrev_b32_e32 v2, 10, v2
	v_mov_b32_e32 v192, v193
	s_or_b32 s29, s4, s5
	v_mul_f32_e32 v132, 0x3fb8aa3b, v3
	v_lshlrev_b32_e32 v3, 1, v0
	v_lshrrev_b32_e32 v0, 2, v0
	v_and_or_b32 v0, v0, 3, v136
	v_and_b32_e32 v3, 32, v3
	v_lshl_add_u32 v0, v0, 6, 0
	v_add3_u32 v145, 0, v2, v1
	v_add3_u32 v147, v0, v3, v4
	v_mov_b32_e32 v194, v193
	v_mov_b32_e32 v195, v193
	v_mov_b32_e32 v196, v193
	v_mov_b32_e32 v197, v193
	v_mov_b32_e32 v198, v193
	v_mov_b32_e32 v199, v193
	v_mov_b32_e32 v200, v193
	v_mov_b32_e32 v201, v193
	v_mov_b32_e32 v202, v193
	v_mov_b32_e32 v203, v193
	v_mov_b32_e32 v204, v193
	v_mov_b32_e32 v205, v193
	v_mov_b32_e32 v206, v193
	v_mov_b32_e32 v207, v193
	v_mov_b64_e32 v[16:17], v[192:193]
	v_mov_b64_e32 v[0:1], v[192:193]
	v_mov_b32_e32 v33, v32
	v_mov_b32_e32 v34, v32
	v_sub_u32_e64 v144, s29, 2 clamp
	v_mov_b32_e32 v35, v32
	v_mov_b32_e32 v36, v32
	v_mov_b32_e32 v37, v32
	v_mov_b32_e32 v38, v32
	v_mov_b32_e32 v39, v32
	v_mov_b32_e32 v40, v32
	v_mov_b32_e32 v41, v32
	v_mov_b32_e32 v42, v32
	v_mov_b32_e32 v43, v32
	v_mov_b32_e32 v44, v32
	v_mov_b32_e32 v45, v32
	v_mov_b32_e32 v46, v32
	v_mov_b32_e32 v47, v32
	s_or_b32 s34, s18, 1
	v_mov_b32_e32 v133, v132
	s_mov_b32 s36, 0
	v_mov_b32_e32 v143, 0
	v_mov_b64_e32 v[18:19], v[194:195]
	v_mov_b64_e32 v[20:21], v[196:197]
	v_mov_b64_e32 v[22:23], v[198:199]
	v_mov_b64_e32 v[24:25], v[200:201]
	v_mov_b64_e32 v[26:27], v[202:203]
	v_mov_b64_e32 v[28:29], v[204:205]
	v_mov_b64_e32 v[30:31], v[206:207]
	v_mov_b64_e32 v[2:3], v[194:195]
	v_mov_b64_e32 v[4:5], v[196:197]
	v_mov_b64_e32 v[6:7], v[198:199]
	v_mov_b64_e32 v[8:9], v[200:201]
	v_mov_b64_e32 v[10:11], v[202:203]
	v_mov_b64_e32 v[12:13], v[204:205]
	v_mov_b64_e32 v[14:15], v[206:207]
	v_mov_b32_e32 v141, 0
	s_branch .LBB0_280

.LBB0_310:
	v_div_scale_f32 v35, s[4:5], v34, v34, 1.0
	v_rcp_f32_e32 v36, v35
	v_div_scale_f32 v37, vcc, 1.0, v34, 1.0
	v_mov_b32_e32 v137, v193
	v_fma_f32 v38, -v35, v36, 1.0
	v_fmac_f32_e32 v36, v38, v36
	v_mul_f32_e32 v38, v37, v36
	v_fma_f32 v39, -v35, v38, v37
	v_fmac_f32_e32 v38, v39, v36
	v_fma_f32 v35, -v35, v38, v37
	v_div_fmas_f32 v35, v35, v36, v38
	v_div_fixup_f32 v34, v35, v34, 1.0
	v_pk_mul_f32 v[16:17], v[16:17], v[34:35] op_sel_hi:[1,0]
	v_pk_mul_f32 v[18:19], v[18:19], v[34:35] op_sel_hi:[1,0]
	v_pk_mul_f32 v[0:1], v[34:35], v[0:1] op_sel_hi:[0,1]
	v_pk_mul_f32 v[2:3], v[34:35], v[2:3] op_sel_hi:[0,1]
	v_lshl_add_u64 v[32:33], v[136:137], 1, v[32:33]
	v_cvt_pk_bf16_f32 v16, v16, v17
	v_cvt_pk_bf16_f32 v17, v18, v19
	v_cvt_pk_bf16_f32 v0, v0, v1
	v_cvt_pk_bf16_f32 v1, v2, v3
	global_store_dwordx2 v[32:33], v[16:17], off
	global_store_dwordx2 v[32:33], v[0:1], off offset:64
	v_pk_mul_f32 v[0:1], v[20:21], v[34:35] op_sel_hi:[1,0]
	v_pk_mul_f32 v[2:3], v[22:23], v[34:35] op_sel_hi:[1,0]
	v_cvt_pk_bf16_f32 v0, v0, v1
	v_cvt_pk_bf16_f32 v1, v2, v3
	v_pk_mul_f32 v[2:3], v[34:35], v[4:5] op_sel_hi:[0,1]
	v_pk_mul_f32 v[4:5], v[34:35], v[6:7] op_sel_hi:[0,1]
	v_cvt_pk_bf16_f32 v2, v2, v3
	v_cvt_pk_bf16_f32 v3, v4, v5
	global_store_dwordx2 v[32:33], v[0:1], off offset:16
	global_store_dwordx2 v[32:33], v[2:3], off offset:80
	v_pk_mul_f32 v[0:1], v[24:25], v[34:35] op_sel_hi:[1,0]
	v_pk_mul_f32 v[2:3], v[26:27], v[34:35] op_sel_hi:[1,0]
	v_cvt_pk_bf16_f32 v0, v0, v1
	v_cvt_pk_bf16_f32 v1, v2, v3
	v_pk_mul_f32 v[2:3], v[34:35], v[8:9] op_sel_hi:[0,1]
	v_pk_mul_f32 v[4:5], v[34:35], v[10:11] op_sel_hi:[0,1]
	v_cvt_pk_bf16_f32 v2, v2, v3
	v_cvt_pk_bf16_f32 v3, v4, v5
	global_store_dwordx2 v[32:33], v[0:1], off offset:32
	global_store_dwordx2 v[32:33], v[2:3], off offset:96
	v_pk_mul_f32 v[0:1], v[28:29], v[34:35] op_sel_hi:[1,0]
	v_pk_mul_f32 v[2:3], v[30:31], v[34:35] op_sel_hi:[1,0]
	v_cvt_pk_bf16_f32 v0, v0, v1
	v_cvt_pk_bf16_f32 v1, v2, v3
	v_pk_mul_f32 v[2:3], v[34:35], v[12:13] op_sel_hi:[0,1]
	v_pk_mul_f32 v[4:5], v[34:35], v[14:15] op_sel_hi:[0,1]
	s_xor_b32 s44, s44, 1
	v_cvt_pk_bf16_f32 v2, v2, v3
	v_cvt_pk_bf16_f32 v3, v4, v5
	global_store_dwordx2 v[32:33], v[0:1], off offset:48
	global_store_dwordx2 v[32:33], v[2:3], off offset:112
	s_and_saveexec_b64 s[4:5], s[40:41]
	s_cbranch_execz .LBB0_271
	s_lshl_b32 s8, s44, 2
	s_add_i32 s8, s8, 0
	s_add_i32 s8, s8, 0x15500
	v_mov_b32_e32 v0, s8
	s_waitcnt vmcnt(0)
	ds_write_b32 v0, v146
	s_branch .LBB0_271
